# diff-attention key loop unrolled 2x with static LDS buffer parity: staging-write and fragment-read addresses folded into immediate offsets (14 fewer VALU + 5 fewer SALU per key tile)
# speedup vs baseline: 1.0206x; 1.0068x over previous
.LBB0_555:
	v_lshlrev_b32_e32 v2, 1, v2
	v_lshlrev_b32_e32 v160, 1, v160
	v_lshlrev_b32_e32 v158, 1, v158
	v_lshlrev_b32_e32 v156, 1, v156
	v_lshlrev_b32_e32 v244, 1, v10
	v_lshlrev_b32_e32 v245, 1, v8
	v_lshlrev_b32_e32 v246, 1, v6
	v_lshlrev_b32_e32 v249, 1, v4
	v_mov_b32_e32 v157, 0
	v_lshl_add_u32 v167, v167, 1, v178
	v_lshl_add_u32 v182, v182, 1, v178
	v_lshl_add_u32 v187, v187, 1, v178
	v_lshl_add_u32 v170, v170, 1, v178
	v_add_u32_e32 v169, v169, v180
	v_add_u32_e32 v185, v185, v180
	v_add_u32_e32 v190, v190, v180
	v_add_u32_e32 v172, v172, v180
	v_add_u32_e32 v206, 0x4800, v174

.Ldq0_p0_addr:
	global_load_dwordx4 v[212:215], v2, s[24:25]
	global_load_dwordx4 v[216:219], v244, s[20:21]
	global_load_dwordx4 v[220:223], v160, s[24:25]
	global_load_dwordx4 v[224:227], v245, s[20:21]
	global_load_dwordx4 v[228:231], v158, s[24:25]
	global_load_dwordx4 v[232:235], v246, s[20:21]
	global_load_dwordx4 v[236:239], v156, s[24:25]
	global_load_dwordx4 v[240:243], v249, s[20:21]
	ds_read_b128 v[4:7], v173
	ds_read_b128 v[8:11], v173 offset:8704
	ds_read_b128 v[14:17], v173 offset:32
	ds_read_b128 v[208:211], v173 offset:8736
	s_waitcnt vmcnt(8)
	s_waitcnt lgkmcnt(3)
	v_mfma_f32_32x32x16_bf16 v[98:113], v[4:7], v[126:129], 0
	ds_read_b128 v[252:255], v173 offset:64
	s_waitcnt lgkmcnt(3)
	v_mfma_f32_32x32x16_bf16 v[82:97], v[8:11], v[126:129], 0
	ds_read_b128 v[4:7], v173 offset:8768
	s_waitcnt lgkmcnt(3)
	v_mfma_f32_32x32x16_bf16 v[98:113], v[14:17], v[122:125], v[98:113]
	ds_read_b128 v[8:11], v173 offset:96
	s_waitcnt lgkmcnt(3)
	v_mfma_f32_32x32x16_bf16 v[82:97], v[208:211], v[122:125], v[82:97]
	ds_read_b128 v[14:17], v173 offset:8800
	s_waitcnt lgkmcnt(3)
	v_mfma_f32_32x32x16_bf16 v[98:113], v[252:255], v[118:121], v[98:113]
	ds_read_b128 v[208:211], v174 offset:34816
	s_waitcnt lgkmcnt(3)
	v_mfma_f32_32x32x16_bf16 v[82:97], v[4:7], v[118:121], v[82:97]
	ds_read_b128 v[252:255], v174 offset:39424
	s_waitcnt lgkmcnt(3)
	v_mfma_f32_32x32x16_bf16 v[98:113], v[8:11], v[114:117], v[98:113]
	ds_read_b128 v[4:7], v174 offset:44032
	s_waitcnt lgkmcnt(3)
	v_mfma_f32_32x32x16_bf16 v[82:97], v[14:17], v[114:117], v[82:97]
	ds_read_b128 v[8:11], v174 offset:48640
	v_add_f32_e32 v159, 0x41000000, v149
	s_nop 6
	v_max3_f32 v207, v98, v99, v100
	v_max3_f32 v13, v101, v102, v103
	v_max3_f32 v207, v207, v104, v105
	v_max3_f32 v13, v13, v106, v107
	v_max3_f32 v207, v207, v108, v109
	v_max3_f32 v13, v13, v110, v111
	v_max3_f32 v207, v207, v112, v113
	v_max3_f32 v13, v13, v82, v83
	v_max3_f32 v207, v207, v84, v85
	v_max3_f32 v13, v13, v86, v87
	v_max3_f32 v207, v207, v88, v89
	v_max3_f32 v13, v13, v90, v91
	v_max3_f32 v207, v207, v92, v93
	v_max3_f32 v13, v13, v94, v95
	v_max3_f32 v207, v207, v96, v97
	v_max_f32_e32 v207, v207, v13
	v_mov_b32_e32 v13, v207
	s_nop 1
	v_permlane32_swap_b32_e32 v207, v13
	v_max_f32_e32 v207, v207, v13
	v_cmp_gt_f32_e32 vcc, v207, v159
	s_cbranch_vccz .Ldq0_p0_nores
	v_max_f32_e32 v207, v149, v207
	v_sub_f32_e32 v250, v149, v207
	v_exp_f32_e32 v250, v250
	v_mov_b32_e32 v149, v207
	v_pk_mul_f32 v[66:67], v[66:67], v[250:251] op_sel_hi:[1,0]
	v_pk_mul_f32 v[68:69], v[68:69], v[250:251] op_sel_hi:[1,0]
	v_pk_mul_f32 v[70:71], v[70:71], v[250:251] op_sel_hi:[1,0]
	v_pk_mul_f32 v[72:73], v[72:73], v[250:251] op_sel_hi:[1,0]
	v_pk_mul_f32 v[74:75], v[74:75], v[250:251] op_sel_hi:[1,0]
	v_pk_mul_f32 v[76:77], v[76:77], v[250:251] op_sel_hi:[1,0]
	v_pk_mul_f32 v[78:79], v[78:79], v[250:251] op_sel_hi:[1,0]
	v_pk_mul_f32 v[80:81], v[80:81], v[250:251] op_sel_hi:[1,0]
	v_pk_mul_f32 v[50:51], v[50:51], v[250:251] op_sel_hi:[1,0]
	v_pk_mul_f32 v[52:53], v[52:53], v[250:251] op_sel_hi:[1,0]
	v_pk_mul_f32 v[54:55], v[54:55], v[250:251] op_sel_hi:[1,0]
	v_pk_mul_f32 v[56:57], v[56:57], v[250:251] op_sel_hi:[1,0]
	v_pk_mul_f32 v[58:59], v[58:59], v[250:251] op_sel_hi:[1,0]
	v_pk_mul_f32 v[60:61], v[60:61], v[250:251] op_sel_hi:[1,0]
	v_pk_mul_f32 v[62:63], v[62:63], v[250:251] op_sel_hi:[1,0]
	v_pk_mul_f32 v[64:65], v[64:65], v[250:251] op_sel_hi:[1,0]
	v_pk_mul_f32 v[34:35], v[34:35], v[250:251] op_sel_hi:[1,0]
	v_pk_mul_f32 v[36:37], v[36:37], v[250:251] op_sel_hi:[1,0]
	v_pk_mul_f32 v[38:39], v[38:39], v[250:251] op_sel_hi:[1,0]
	v_pk_mul_f32 v[40:41], v[40:41], v[250:251] op_sel_hi:[1,0]
	v_pk_mul_f32 v[42:43], v[42:43], v[250:251] op_sel_hi:[1,0]
	v_pk_mul_f32 v[44:45], v[44:45], v[250:251] op_sel_hi:[1,0]
	v_pk_mul_f32 v[46:47], v[46:47], v[250:251] op_sel_hi:[1,0]
	v_pk_mul_f32 v[48:49], v[48:49], v[250:251] op_sel_hi:[1,0]
	v_pk_mul_f32 v[18:19], v[18:19], v[250:251] op_sel_hi:[1,0]
	v_pk_mul_f32 v[20:21], v[20:21], v[250:251] op_sel_hi:[1,0]
	v_pk_mul_f32 v[22:23], v[22:23], v[250:251] op_sel_hi:[1,0]
	v_pk_mul_f32 v[24:25], v[24:25], v[250:251] op_sel_hi:[1,0]
	v_pk_mul_f32 v[26:27], v[26:27], v[250:251] op_sel_hi:[1,0]
	v_pk_mul_f32 v[28:29], v[28:29], v[250:251] op_sel_hi:[1,0]
	v_pk_mul_f32 v[30:31], v[30:31], v[250:251] op_sel_hi:[1,0]
	v_pk_mul_f32 v[32:33], v[32:33], v[250:251] op_sel_hi:[1,0]
	v_mul_f32_e32 v12, v12, v250
	v_mul_f32_e32 v157, v157, v250
.Ldq0_p0_nores:
	v_sub_f32_e32 v250, v98, v149
	v_exp_f32_e32 v98, v250
	v_sub_f32_e32 v159, v99, v149
	v_exp_f32_e32 v99, v159
	v_sub_f32_e32 v250, v100, v149
	v_exp_f32_e32 v100, v250
	v_sub_f32_e32 v159, v101, v149
	v_exp_f32_e32 v101, v159
	v_sub_f32_e32 v250, v102, v149
	v_exp_f32_e32 v102, v250
	v_sub_f32_e32 v159, v103, v149
	v_exp_f32_e32 v103, v159
	v_sub_f32_e32 v250, v104, v149
	v_exp_f32_e32 v104, v250
	v_sub_f32_e32 v159, v105, v149
	v_exp_f32_e32 v105, v159
	v_add_f32_e32 v12, v12, v98
	v_add_f32_e32 v157, v157, v99
	v_add_f32_e32 v12, v12, v100
	v_add_f32_e32 v157, v157, v101
	v_add_f32_e32 v12, v12, v102
	v_add_f32_e32 v157, v157, v103
	v_add_f32_e32 v12, v12, v104
	v_add_f32_e32 v157, v157, v105
	v_cvt_pk_bf16_f32 v98, v98, v99
	v_cvt_pk_bf16_f32 v99, v100, v101
	v_cvt_pk_bf16_f32 v100, v102, v103
	v_cvt_pk_bf16_f32 v101, v104, v105
	ds_read_b128 v[14:17], v174 offset:34848
	s_waitcnt lgkmcnt(4)
	v_mfma_f32_32x32x16_bf16 v[66:81], v[208:211], v[98:101], v[66:81]
	v_sub_f32_e32 v250, v106, v149
	v_exp_f32_e32 v106, v250
	v_sub_f32_e32 v159, v107, v149
	v_exp_f32_e32 v107, v159
	v_sub_f32_e32 v250, v108, v149
	v_exp_f32_e32 v108, v250
	v_sub_f32_e32 v159, v109, v149
	v_exp_f32_e32 v109, v159
	ds_read_b128 v[208:211], v174 offset:39456
	s_waitcnt lgkmcnt(4)
	v_mfma_f32_32x32x16_bf16 v[50:65], v[252:255], v[98:101], v[50:65]
	v_sub_f32_e32 v250, v110, v149
	v_exp_f32_e32 v110, v250
	v_sub_f32_e32 v159, v111, v149
	v_exp_f32_e32 v111, v159
	v_sub_f32_e32 v250, v112, v149
	v_exp_f32_e32 v112, v250
	v_sub_f32_e32 v159, v113, v149
	v_exp_f32_e32 v113, v159
	ds_read_b128 v[252:255], v174 offset:44064
	s_waitcnt lgkmcnt(4)
	v_mfma_f32_32x32x16_bf16 v[34:49], v[4:7], v[98:101], v[34:49]
	v_add_f32_e32 v12, v12, v106
	v_add_f32_e32 v157, v157, v107
	v_add_f32_e32 v12, v12, v108
	v_add_f32_e32 v157, v157, v109
	v_add_f32_e32 v12, v12, v110
	v_add_f32_e32 v157, v157, v111
	v_add_f32_e32 v12, v12, v112
	v_add_f32_e32 v157, v157, v113
	ds_read_b128 v[4:7], v174 offset:48672
	s_waitcnt lgkmcnt(4)
	v_mfma_f32_32x32x16_bf16 v[18:33], v[8:11], v[98:101], v[18:33]
	v_cvt_pk_bf16_f32 v106, v106, v107
	v_cvt_pk_bf16_f32 v107, v108, v109
	v_cvt_pk_bf16_f32 v108, v110, v111
	v_cvt_pk_bf16_f32 v109, v112, v113
	ds_read_b128 v[8:11], v174 offset:34880
	s_waitcnt lgkmcnt(4)
	v_mfma_f32_32x32x16_bf16 v[66:81], v[14:17], v[106:109], v[66:81]
	v_sub_f32_e32 v250, v82, v149
	v_exp_f32_e32 v82, v250
	v_sub_f32_e32 v159, v83, v149
	v_exp_f32_e32 v83, v159
	v_sub_f32_e32 v250, v84, v149
	v_exp_f32_e32 v84, v250
	v_sub_f32_e32 v159, v85, v149
	v_exp_f32_e32 v85, v159
	ds_read_b128 v[14:17], v174 offset:39488
	s_waitcnt lgkmcnt(4)
	v_mfma_f32_32x32x16_bf16 v[50:65], v[208:211], v[106:109], v[50:65]
	v_sub_f32_e32 v250, v86, v149
	v_exp_f32_e32 v86, v250
	v_sub_f32_e32 v159, v87, v149
	v_exp_f32_e32 v87, v159
	v_sub_f32_e32 v250, v88, v149
	v_exp_f32_e32 v88, v250
	v_sub_f32_e32 v159, v89, v149
	v_exp_f32_e32 v89, v159
	ds_read_b128 v[208:211], v174 offset:44096
	s_waitcnt lgkmcnt(4)
	v_mfma_f32_32x32x16_bf16 v[34:49], v[252:255], v[106:109], v[34:49]
	v_add_f32_e32 v12, v12, v82
	v_add_f32_e32 v157, v157, v83
	v_add_f32_e32 v12, v12, v84
	v_add_f32_e32 v157, v157, v85
	v_add_f32_e32 v12, v12, v86
	v_add_f32_e32 v157, v157, v87
	v_add_f32_e32 v12, v12, v88
	v_add_f32_e32 v157, v157, v89
	ds_read_b128 v[252:255], v174 offset:48704
	s_waitcnt lgkmcnt(4)
	v_mfma_f32_32x32x16_bf16 v[18:33], v[4:7], v[106:109], v[18:33]
	v_cvt_pk_bf16_f32 v82, v82, v83
	v_cvt_pk_bf16_f32 v83, v84, v85
	v_cvt_pk_bf16_f32 v84, v86, v87
	v_cvt_pk_bf16_f32 v85, v88, v89
	ds_read_b128 v[4:7], v174 offset:34912
	s_waitcnt lgkmcnt(4)
	v_mfma_f32_32x32x16_bf16 v[66:81], v[8:11], v[82:85], v[66:81]
	v_sub_f32_e32 v250, v90, v149
	v_exp_f32_e32 v90, v250
	v_sub_f32_e32 v159, v91, v149
	v_exp_f32_e32 v91, v159
	v_sub_f32_e32 v250, v92, v149
	v_exp_f32_e32 v92, v250
	v_sub_f32_e32 v159, v93, v149
	v_exp_f32_e32 v93, v159
	ds_read_b128 v[8:11], v174 offset:39520
	s_waitcnt lgkmcnt(4)
	v_mfma_f32_32x32x16_bf16 v[50:65], v[14:17], v[82:85], v[50:65]
	v_sub_f32_e32 v250, v94, v149
	v_exp_f32_e32 v94, v250
	v_sub_f32_e32 v159, v95, v149
	v_exp_f32_e32 v95, v159
	v_sub_f32_e32 v250, v96, v149
	v_exp_f32_e32 v96, v250
	v_sub_f32_e32 v159, v97, v149
	v_exp_f32_e32 v97, v159
	s_waitcnt vmcnt(7)
	ds_write_b128 v167, v[212:215] offset:17408
	s_waitcnt vmcnt(6)
	ds_write_b128 v169, v[216:219] offset:53248
	ds_read_b128 v[14:17], v174 offset:44128
	s_waitcnt lgkmcnt(6)
	v_mfma_f32_32x32x16_bf16 v[34:49], v[208:211], v[82:85], v[34:49]
	v_add_f32_e32 v12, v12, v90
	v_add_f32_e32 v157, v157, v91
	v_add_f32_e32 v12, v12, v92
	v_add_f32_e32 v157, v157, v93
	v_add_f32_e32 v12, v12, v94
	v_add_f32_e32 v157, v157, v95
	v_add_f32_e32 v12, v12, v96
	v_add_f32_e32 v157, v157, v97
	ds_read_b128 v[208:211], v174 offset:48736
	s_waitcnt lgkmcnt(6)
	v_mfma_f32_32x32x16_bf16 v[18:33], v[252:255], v[82:85], v[18:33]
	v_cvt_pk_bf16_f32 v90, v90, v91
	v_cvt_pk_bf16_f32 v91, v92, v93
	v_cvt_pk_bf16_f32 v92, v94, v95
	v_cvt_pk_bf16_f32 v93, v96, v97
	s_waitcnt vmcnt(5)
	ds_write_b128 v182, v[220:223] offset:17408
	s_waitcnt vmcnt(4)
	ds_write_b128 v185, v[224:227] offset:53248
	s_waitcnt lgkmcnt(7)
	v_mfma_f32_32x32x16_bf16 v[66:81], v[4:7], v[90:93], v[66:81]
	s_waitcnt vmcnt(3)
	ds_write_b128 v187, v[228:231] offset:17408
	s_waitcnt vmcnt(2)
	ds_write_b128 v190, v[232:235] offset:53248
	s_waitcnt lgkmcnt(8)
	v_mfma_f32_32x32x16_bf16 v[50:65], v[8:11], v[90:93], v[50:65]
	s_waitcnt lgkmcnt(5)
	v_mfma_f32_32x32x16_bf16 v[34:49], v[14:17], v[90:93], v[34:49]
	s_waitcnt vmcnt(1)
	ds_write_b128 v170, v[236:239] offset:17408
	s_waitcnt vmcnt(0)
	ds_write_b128 v172, v[240:243] offset:53248
	s_waitcnt lgkmcnt(6)
	v_mfma_f32_32x32x16_bf16 v[18:33], v[208:211], v[90:93], v[18:33]
	s_waitcnt lgkmcnt(0)
	s_barrier
	s_cmp_eq_u32 s38, s41
	s_cbranch_scc1 .Ldq0_exit
	s_mov_b32 s42, s41

.Ldq0_p1_addr:
	global_load_dwordx4 v[212:215], v2, s[24:25]
	global_load_dwordx4 v[216:219], v244, s[20:21]
	global_load_dwordx4 v[220:223], v160, s[24:25]
	global_load_dwordx4 v[224:227], v245, s[20:21]
	global_load_dwordx4 v[228:231], v158, s[24:25]
	global_load_dwordx4 v[232:235], v246, s[20:21]
	global_load_dwordx4 v[236:239], v156, s[24:25]
	global_load_dwordx4 v[240:243], v249, s[20:21]
	ds_read_b128 v[4:7], v173 offset:17408
	ds_read_b128 v[8:11], v173 offset:26112
	ds_read_b128 v[14:17], v173 offset:17440
	ds_read_b128 v[208:211], v173 offset:26144
	s_waitcnt vmcnt(8)
	s_waitcnt lgkmcnt(3)
	v_mfma_f32_32x32x16_bf16 v[98:113], v[4:7], v[126:129], 0
	ds_read_b128 v[252:255], v173 offset:17472
	s_waitcnt lgkmcnt(3)
	v_mfma_f32_32x32x16_bf16 v[82:97], v[8:11], v[126:129], 0
	ds_read_b128 v[4:7], v173 offset:26176
	s_waitcnt lgkmcnt(3)
	v_mfma_f32_32x32x16_bf16 v[98:113], v[14:17], v[122:125], v[98:113]
	ds_read_b128 v[8:11], v173 offset:17504
	s_waitcnt lgkmcnt(3)
	v_mfma_f32_32x32x16_bf16 v[82:97], v[208:211], v[122:125], v[82:97]
	ds_read_b128 v[14:17], v173 offset:26208
	s_waitcnt lgkmcnt(3)
	v_mfma_f32_32x32x16_bf16 v[98:113], v[252:255], v[118:121], v[98:113]
	ds_read_b128 v[208:211], v206 offset:34816
	s_waitcnt lgkmcnt(3)
	v_mfma_f32_32x32x16_bf16 v[82:97], v[4:7], v[118:121], v[82:97]
	ds_read_b128 v[252:255], v206 offset:39424
	s_waitcnt lgkmcnt(3)
	v_mfma_f32_32x32x16_bf16 v[98:113], v[8:11], v[114:117], v[98:113]
	ds_read_b128 v[4:7], v206 offset:44032
	s_waitcnt lgkmcnt(3)
	v_mfma_f32_32x32x16_bf16 v[82:97], v[14:17], v[114:117], v[82:97]
	ds_read_b128 v[8:11], v206 offset:48640
	v_add_f32_e32 v159, 0x41000000, v149
	s_nop 6
	v_max3_f32 v207, v98, v99, v100
	v_max3_f32 v13, v101, v102, v103
	v_max3_f32 v207, v207, v104, v105
	v_max3_f32 v13, v13, v106, v107
	v_max3_f32 v207, v207, v108, v109
	v_max3_f32 v13, v13, v110, v111
	v_max3_f32 v207, v207, v112, v113
	v_max3_f32 v13, v13, v82, v83
	v_max3_f32 v207, v207, v84, v85
	v_max3_f32 v13, v13, v86, v87
	v_max3_f32 v207, v207, v88, v89
	v_max3_f32 v13, v13, v90, v91
	v_max3_f32 v207, v207, v92, v93
	v_max3_f32 v13, v13, v94, v95
	v_max3_f32 v207, v207, v96, v97
	v_max_f32_e32 v207, v207, v13
	v_mov_b32_e32 v13, v207
	s_nop 1
	v_permlane32_swap_b32_e32 v207, v13
	v_max_f32_e32 v207, v207, v13
	v_cmp_gt_f32_e32 vcc, v207, v159
	s_cbranch_vccz .Ldq0_p1_nores
	v_max_f32_e32 v207, v149, v207
	v_sub_f32_e32 v250, v149, v207
	v_exp_f32_e32 v250, v250
	v_mov_b32_e32 v149, v207
	v_pk_mul_f32 v[66:67], v[66:67], v[250:251] op_sel_hi:[1,0]
	v_pk_mul_f32 v[68:69], v[68:69], v[250:251] op_sel_hi:[1,0]
	v_pk_mul_f32 v[70:71], v[70:71], v[250:251] op_sel_hi:[1,0]
	v_pk_mul_f32 v[72:73], v[72:73], v[250:251] op_sel_hi:[1,0]
	v_pk_mul_f32 v[74:75], v[74:75], v[250:251] op_sel_hi:[1,0]
	v_pk_mul_f32 v[76:77], v[76:77], v[250:251] op_sel_hi:[1,0]
	v_pk_mul_f32 v[78:79], v[78:79], v[250:251] op_sel_hi:[1,0]
	v_pk_mul_f32 v[80:81], v[80:81], v[250:251] op_sel_hi:[1,0]
	v_pk_mul_f32 v[50:51], v[50:51], v[250:251] op_sel_hi:[1,0]
	v_pk_mul_f32 v[52:53], v[52:53], v[250:251] op_sel_hi:[1,0]
	v_pk_mul_f32 v[54:55], v[54:55], v[250:251] op_sel_hi:[1,0]
	v_pk_mul_f32 v[56:57], v[56:57], v[250:251] op_sel_hi:[1,0]
	v_pk_mul_f32 v[58:59], v[58:59], v[250:251] op_sel_hi:[1,0]
	v_pk_mul_f32 v[60:61], v[60:61], v[250:251] op_sel_hi:[1,0]
	v_pk_mul_f32 v[62:63], v[62:63], v[250:251] op_sel_hi:[1,0]
	v_pk_mul_f32 v[64:65], v[64:65], v[250:251] op_sel_hi:[1,0]
	v_pk_mul_f32 v[34:35], v[34:35], v[250:251] op_sel_hi:[1,0]
	v_pk_mul_f32 v[36:37], v[36:37], v[250:251] op_sel_hi:[1,0]
	v_pk_mul_f32 v[38:39], v[38:39], v[250:251] op_sel_hi:[1,0]
	v_pk_mul_f32 v[40:41], v[40:41], v[250:251] op_sel_hi:[1,0]
	v_pk_mul_f32 v[42:43], v[42:43], v[250:251] op_sel_hi:[1,0]
	v_pk_mul_f32 v[44:45], v[44:45], v[250:251] op_sel_hi:[1,0]
	v_pk_mul_f32 v[46:47], v[46:47], v[250:251] op_sel_hi:[1,0]
	v_pk_mul_f32 v[48:49], v[48:49], v[250:251] op_sel_hi:[1,0]
	v_pk_mul_f32 v[18:19], v[18:19], v[250:251] op_sel_hi:[1,0]
	v_pk_mul_f32 v[20:21], v[20:21], v[250:251] op_sel_hi:[1,0]
	v_pk_mul_f32 v[22:23], v[22:23], v[250:251] op_sel_hi:[1,0]
	v_pk_mul_f32 v[24:25], v[24:25], v[250:251] op_sel_hi:[1,0]
	v_pk_mul_f32 v[26:27], v[26:27], v[250:251] op_sel_hi:[1,0]
	v_pk_mul_f32 v[28:29], v[28:29], v[250:251] op_sel_hi:[1,0]
	v_pk_mul_f32 v[30:31], v[30:31], v[250:251] op_sel_hi:[1,0]
	v_pk_mul_f32 v[32:33], v[32:33], v[250:251] op_sel_hi:[1,0]
	v_mul_f32_e32 v12, v12, v250
	v_mul_f32_e32 v157, v157, v250
.Ldq0_p1_nores:
	v_sub_f32_e32 v250, v98, v149
	v_exp_f32_e32 v98, v250
	v_sub_f32_e32 v159, v99, v149
	v_exp_f32_e32 v99, v159
	v_sub_f32_e32 v250, v100, v149
	v_exp_f32_e32 v100, v250
	v_sub_f32_e32 v159, v101, v149
	v_exp_f32_e32 v101, v159
	v_sub_f32_e32 v250, v102, v149
	v_exp_f32_e32 v102, v250
	v_sub_f32_e32 v159, v103, v149
	v_exp_f32_e32 v103, v159
	v_sub_f32_e32 v250, v104, v149
	v_exp_f32_e32 v104, v250
	v_sub_f32_e32 v159, v105, v149
	v_exp_f32_e32 v105, v159
	v_add_f32_e32 v12, v12, v98
	v_add_f32_e32 v157, v157, v99
	v_add_f32_e32 v12, v12, v100
	v_add_f32_e32 v157, v157, v101
	v_add_f32_e32 v12, v12, v102
	v_add_f32_e32 v157, v157, v103
	v_add_f32_e32 v12, v12, v104
	v_add_f32_e32 v157, v157, v105
	v_cvt_pk_bf16_f32 v98, v98, v99
	v_cvt_pk_bf16_f32 v99, v100, v101
	v_cvt_pk_bf16_f32 v100, v102, v103
	v_cvt_pk_bf16_f32 v101, v104, v105
	ds_read_b128 v[14:17], v206 offset:34848
	s_waitcnt lgkmcnt(4)
	v_mfma_f32_32x32x16_bf16 v[66:81], v[208:211], v[98:101], v[66:81]
	v_sub_f32_e32 v250, v106, v149
	v_exp_f32_e32 v106, v250
	v_sub_f32_e32 v159, v107, v149
	v_exp_f32_e32 v107, v159
	v_sub_f32_e32 v250, v108, v149
	v_exp_f32_e32 v108, v250
	v_sub_f32_e32 v159, v109, v149
	v_exp_f32_e32 v109, v159
	ds_read_b128 v[208:211], v206 offset:39456
	s_waitcnt lgkmcnt(4)
	v_mfma_f32_32x32x16_bf16 v[50:65], v[252:255], v[98:101], v[50:65]
	v_sub_f32_e32 v250, v110, v149
	v_exp_f32_e32 v110, v250
	v_sub_f32_e32 v159, v111, v149
	v_exp_f32_e32 v111, v159
	v_sub_f32_e32 v250, v112, v149
	v_exp_f32_e32 v112, v250
	v_sub_f32_e32 v159, v113, v149
	v_exp_f32_e32 v113, v159
	ds_read_b128 v[252:255], v206 offset:44064
	s_waitcnt lgkmcnt(4)
	v_mfma_f32_32x32x16_bf16 v[34:49], v[4:7], v[98:101], v[34:49]
	v_add_f32_e32 v12, v12, v106
	v_add_f32_e32 v157, v157, v107
	v_add_f32_e32 v12, v12, v108
	v_add_f32_e32 v157, v157, v109
	v_add_f32_e32 v12, v12, v110
	v_add_f32_e32 v157, v157, v111
	v_add_f32_e32 v12, v12, v112
	v_add_f32_e32 v157, v157, v113
	ds_read_b128 v[4:7], v206 offset:48672
	s_waitcnt lgkmcnt(4)
	v_mfma_f32_32x32x16_bf16 v[18:33], v[8:11], v[98:101], v[18:33]
	v_cvt_pk_bf16_f32 v106, v106, v107
	v_cvt_pk_bf16_f32 v107, v108, v109
	v_cvt_pk_bf16_f32 v108, v110, v111
	v_cvt_pk_bf16_f32 v109, v112, v113
	ds_read_b128 v[8:11], v206 offset:34880
	s_waitcnt lgkmcnt(4)
	v_mfma_f32_32x32x16_bf16 v[66:81], v[14:17], v[106:109], v[66:81]
	v_sub_f32_e32 v250, v82, v149
	v_exp_f32_e32 v82, v250
	v_sub_f32_e32 v159, v83, v149
	v_exp_f32_e32 v83, v159
	v_sub_f32_e32 v250, v84, v149
	v_exp_f32_e32 v84, v250
	v_sub_f32_e32 v159, v85, v149
	v_exp_f32_e32 v85, v159
	ds_read_b128 v[14:17], v206 offset:39488
	s_waitcnt lgkmcnt(4)
	v_mfma_f32_32x32x16_bf16 v[50:65], v[208:211], v[106:109], v[50:65]
	v_sub_f32_e32 v250, v86, v149
	v_exp_f32_e32 v86, v250
	v_sub_f32_e32 v159, v87, v149
	v_exp_f32_e32 v87, v159
	v_sub_f32_e32 v250, v88, v149
	v_exp_f32_e32 v88, v250
	v_sub_f32_e32 v159, v89, v149
	v_exp_f32_e32 v89, v159
	ds_read_b128 v[208:211], v206 offset:44096
	s_waitcnt lgkmcnt(4)
	v_mfma_f32_32x32x16_bf16 v[34:49], v[252:255], v[106:109], v[34:49]
	v_add_f32_e32 v12, v12, v82
	v_add_f32_e32 v157, v157, v83
	v_add_f32_e32 v12, v12, v84
	v_add_f32_e32 v157, v157, v85
	v_add_f32_e32 v12, v12, v86
	v_add_f32_e32 v157, v157, v87
	v_add_f32_e32 v12, v12, v88
	v_add_f32_e32 v157, v157, v89
	ds_read_b128 v[252:255], v206 offset:48704
	s_waitcnt lgkmcnt(4)
	v_mfma_f32_32x32x16_bf16 v[18:33], v[4:7], v[106:109], v[18:33]
	v_cvt_pk_bf16_f32 v82, v82, v83
	v_cvt_pk_bf16_f32 v83, v84, v85
	v_cvt_pk_bf16_f32 v84, v86, v87
	v_cvt_pk_bf16_f32 v85, v88, v89
	ds_read_b128 v[4:7], v206 offset:34912
	s_waitcnt lgkmcnt(4)
	v_mfma_f32_32x32x16_bf16 v[66:81], v[8:11], v[82:85], v[66:81]
	v_sub_f32_e32 v250, v90, v149
	v_exp_f32_e32 v90, v250
	v_sub_f32_e32 v159, v91, v149
	v_exp_f32_e32 v91, v159
	v_sub_f32_e32 v250, v92, v149
	v_exp_f32_e32 v92, v250
	v_sub_f32_e32 v159, v93, v149
	v_exp_f32_e32 v93, v159
	ds_read_b128 v[8:11], v206 offset:39520
	s_waitcnt lgkmcnt(4)
	v_mfma_f32_32x32x16_bf16 v[50:65], v[14:17], v[82:85], v[50:65]
	v_sub_f32_e32 v250, v94, v149
	v_exp_f32_e32 v94, v250
	v_sub_f32_e32 v159, v95, v149
	v_exp_f32_e32 v95, v159
	v_sub_f32_e32 v250, v96, v149
	v_exp_f32_e32 v96, v250
	v_sub_f32_e32 v159, v97, v149
	v_exp_f32_e32 v97, v159
	s_waitcnt vmcnt(7)
	ds_write_b128 v167, v[212:215]
	s_waitcnt vmcnt(6)
	ds_write_b128 v169, v[216:219] offset:34816
	ds_read_b128 v[14:17], v206 offset:44128
	s_waitcnt lgkmcnt(6)
	v_mfma_f32_32x32x16_bf16 v[34:49], v[208:211], v[82:85], v[34:49]
	v_add_f32_e32 v12, v12, v90
	v_add_f32_e32 v157, v157, v91
	v_add_f32_e32 v12, v12, v92
	v_add_f32_e32 v157, v157, v93
	v_add_f32_e32 v12, v12, v94
	v_add_f32_e32 v157, v157, v95
	v_add_f32_e32 v12, v12, v96
	v_add_f32_e32 v157, v157, v97
	ds_read_b128 v[208:211], v206 offset:48736
	s_waitcnt lgkmcnt(6)
	v_mfma_f32_32x32x16_bf16 v[18:33], v[252:255], v[82:85], v[18:33]
	v_cvt_pk_bf16_f32 v90, v90, v91
	v_cvt_pk_bf16_f32 v91, v92, v93
	v_cvt_pk_bf16_f32 v92, v94, v95
	v_cvt_pk_bf16_f32 v93, v96, v97
	s_waitcnt vmcnt(5)
	ds_write_b128 v182, v[220:223]
	s_waitcnt vmcnt(4)
	ds_write_b128 v185, v[224:227] offset:34816
	s_waitcnt lgkmcnt(7)
	v_mfma_f32_32x32x16_bf16 v[66:81], v[4:7], v[90:93], v[66:81]
	s_waitcnt vmcnt(3)
	ds_write_b128 v187, v[228:231]
	s_waitcnt vmcnt(2)
	ds_write_b128 v190, v[232:235] offset:34816
	s_waitcnt lgkmcnt(8)
	v_mfma_f32_32x32x16_bf16 v[50:65], v[8:11], v[90:93], v[50:65]
	s_waitcnt lgkmcnt(5)
	v_mfma_f32_32x32x16_bf16 v[34:49], v[14:17], v[90:93], v[34:49]
	s_waitcnt vmcnt(1)
	ds_write_b128 v170, v[236:239]
	s_waitcnt vmcnt(0)
	ds_write_b128 v172, v[240:243] offset:34816
	s_waitcnt lgkmcnt(6)
	v_mfma_f32_32x32x16_bf16 v[18:33], v[208:211], v[90:93], v[18:33]
	s_waitcnt lgkmcnt(0)
	s_barrier
	s_cmp_eq_u32 s38, s41
	s_cbranch_scc1 .Ldq0_exit
	s_mov_b32 s42, s41
	s_branch .Ldq0_p0_top
.Ldq0_exit:
	v_sub_u32_e32 v167, v167, v178
	v_lshrrev_b32_e32 v167, 1, v167
	v_sub_u32_e32 v182, v182, v178
	v_lshrrev_b32_e32 v182, 1, v182
	v_sub_u32_e32 v187, v187, v178
	v_lshrrev_b32_e32 v187, 1, v187
	v_sub_u32_e32 v170, v170, v178
	v_lshrrev_b32_e32 v170, 1, v170
	v_sub_u32_e32 v169, v169, v180
	v_sub_u32_e32 v185, v185, v180
	v_sub_u32_e32 v190, v190, v180
	v_sub_u32_e32 v172, v172, v180
	v_add_f32_e32 v12, v12, v157

.LBB0_1447:
	v_lshlrev_b32_e32 v2, 1, v2
	v_lshlrev_b32_e32 v162, 1, v162
	v_lshlrev_b32_e32 v160, 1, v160
	v_lshlrev_b32_e32 v158, 1, v158
	v_lshlrev_b32_e32 v244, 1, v10
	v_lshlrev_b32_e32 v245, 1, v8
	v_lshlrev_b32_e32 v246, 1, v6
	v_lshlrev_b32_e32 v249, 1, v4
	v_mov_b32_e32 v159, 0
	v_lshl_add_u32 v168, v168, 1, v179
	v_lshl_add_u32 v183, v183, 1, v179
	v_lshl_add_u32 v190, v190, 1, v179
	v_lshl_add_u32 v171, v171, 1, v179
	v_add_u32_e32 v170, v170, v181
	v_add_u32_e32 v188, v188, v181
	v_add_u32_e32 v193, v193, v181
	v_add_u32_e32 v173, v173, v181
	v_add_u32_e32 v163, 0x4800, v175

.Ldq1_p0_addr:
	global_load_dwordx4 v[212:215], v2, s[24:25]
	global_load_dwordx4 v[216:219], v244, s[20:21]
	global_load_dwordx4 v[220:223], v162, s[24:25]
	global_load_dwordx4 v[224:227], v245, s[20:21]
	global_load_dwordx4 v[228:231], v160, s[24:25]
	global_load_dwordx4 v[232:235], v246, s[20:21]
	global_load_dwordx4 v[236:239], v158, s[24:25]
	global_load_dwordx4 v[240:243], v249, s[20:21]
	ds_read_b128 v[4:7], v174
	ds_read_b128 v[8:11], v174 offset:8704
	ds_read_b128 v[14:17], v174 offset:32
	ds_read_b128 v[208:211], v174 offset:8736
	s_waitcnt vmcnt(8)
	s_waitcnt lgkmcnt(3)
	v_mfma_f32_32x32x16_bf16 v[98:113], v[4:7], v[126:129], 0
	ds_read_b128 v[252:255], v174 offset:64
	s_waitcnt lgkmcnt(3)
	v_mfma_f32_32x32x16_bf16 v[82:97], v[8:11], v[126:129], 0
	ds_read_b128 v[4:7], v174 offset:8768
	s_waitcnt lgkmcnt(3)
	v_mfma_f32_32x32x16_bf16 v[98:113], v[14:17], v[122:125], v[98:113]
	ds_read_b128 v[8:11], v174 offset:96
	s_waitcnt lgkmcnt(3)
	v_mfma_f32_32x32x16_bf16 v[82:97], v[208:211], v[122:125], v[82:97]
	ds_read_b128 v[14:17], v174 offset:8800
	s_waitcnt lgkmcnt(3)
	v_mfma_f32_32x32x16_bf16 v[98:113], v[252:255], v[118:121], v[98:113]
	ds_read_b128 v[208:211], v175 offset:34816
	s_waitcnt lgkmcnt(3)
	v_mfma_f32_32x32x16_bf16 v[82:97], v[4:7], v[118:121], v[82:97]
	ds_read_b128 v[252:255], v175 offset:39424
	s_waitcnt lgkmcnt(3)
	v_mfma_f32_32x32x16_bf16 v[98:113], v[8:11], v[114:117], v[98:113]
	ds_read_b128 v[4:7], v175 offset:44032
	s_waitcnt lgkmcnt(3)
	v_mfma_f32_32x32x16_bf16 v[82:97], v[14:17], v[114:117], v[82:97]
	ds_read_b128 v[8:11], v175 offset:48640
	v_add_f32_e32 v161, 0x41000000, v151
	s_nop 6
	v_max3_f32 v251, v98, v99, v100
	v_max3_f32 v13, v101, v102, v103
	v_max3_f32 v251, v251, v104, v105
	v_max3_f32 v13, v13, v106, v107
	v_max3_f32 v251, v251, v108, v109
	v_max3_f32 v13, v13, v110, v111
	v_max3_f32 v251, v251, v112, v113
	v_max3_f32 v13, v13, v82, v83
	v_max3_f32 v251, v251, v84, v85
	v_max3_f32 v13, v13, v86, v87
	v_max3_f32 v251, v251, v88, v89
	v_max3_f32 v13, v13, v90, v91
	v_max3_f32 v251, v251, v92, v93
	v_max3_f32 v13, v13, v94, v95
	v_max3_f32 v251, v251, v96, v97
	v_max_f32_e32 v251, v251, v13
	v_mov_b32_e32 v13, v251
	s_nop 1
	v_permlane32_swap_b32_e32 v251, v13
	v_max_f32_e32 v251, v251, v13
	v_cmp_gt_f32_e32 vcc, v251, v161
	s_cbranch_vccz .Ldq1_p0_nores
	v_max_f32_e32 v251, v151, v251
	v_sub_f32_e32 v250, v151, v251
	v_exp_f32_e32 v250, v250
	v_mov_b32_e32 v151, v251
	v_pk_mul_f32 v[66:67], v[66:67], v[250:251] op_sel_hi:[1,0]
	v_pk_mul_f32 v[68:69], v[68:69], v[250:251] op_sel_hi:[1,0]
	v_pk_mul_f32 v[70:71], v[70:71], v[250:251] op_sel_hi:[1,0]
	v_pk_mul_f32 v[72:73], v[72:73], v[250:251] op_sel_hi:[1,0]
	v_pk_mul_f32 v[74:75], v[74:75], v[250:251] op_sel_hi:[1,0]
	v_pk_mul_f32 v[76:77], v[76:77], v[250:251] op_sel_hi:[1,0]
	v_pk_mul_f32 v[78:79], v[78:79], v[250:251] op_sel_hi:[1,0]
	v_pk_mul_f32 v[80:81], v[80:81], v[250:251] op_sel_hi:[1,0]
	v_pk_mul_f32 v[50:51], v[50:51], v[250:251] op_sel_hi:[1,0]
	v_pk_mul_f32 v[52:53], v[52:53], v[250:251] op_sel_hi:[1,0]
	v_pk_mul_f32 v[54:55], v[54:55], v[250:251] op_sel_hi:[1,0]
	v_pk_mul_f32 v[56:57], v[56:57], v[250:251] op_sel_hi:[1,0]
	v_pk_mul_f32 v[58:59], v[58:59], v[250:251] op_sel_hi:[1,0]
	v_pk_mul_f32 v[60:61], v[60:61], v[250:251] op_sel_hi:[1,0]
	v_pk_mul_f32 v[62:63], v[62:63], v[250:251] op_sel_hi:[1,0]
	v_pk_mul_f32 v[64:65], v[64:65], v[250:251] op_sel_hi:[1,0]
	v_pk_mul_f32 v[34:35], v[34:35], v[250:251] op_sel_hi:[1,0]
	v_pk_mul_f32 v[36:37], v[36:37], v[250:251] op_sel_hi:[1,0]
	v_pk_mul_f32 v[38:39], v[38:39], v[250:251] op_sel_hi:[1,0]
	v_pk_mul_f32 v[40:41], v[40:41], v[250:251] op_sel_hi:[1,0]
	v_pk_mul_f32 v[42:43], v[42:43], v[250:251] op_sel_hi:[1,0]
	v_pk_mul_f32 v[44:45], v[44:45], v[250:251] op_sel_hi:[1,0]
	v_pk_mul_f32 v[46:47], v[46:47], v[250:251] op_sel_hi:[1,0]
	v_pk_mul_f32 v[48:49], v[48:49], v[250:251] op_sel_hi:[1,0]
	v_pk_mul_f32 v[18:19], v[18:19], v[250:251] op_sel_hi:[1,0]
	v_pk_mul_f32 v[20:21], v[20:21], v[250:251] op_sel_hi:[1,0]
	v_pk_mul_f32 v[22:23], v[22:23], v[250:251] op_sel_hi:[1,0]
	v_pk_mul_f32 v[24:25], v[24:25], v[250:251] op_sel_hi:[1,0]
	v_pk_mul_f32 v[26:27], v[26:27], v[250:251] op_sel_hi:[1,0]
	v_pk_mul_f32 v[28:29], v[28:29], v[250:251] op_sel_hi:[1,0]
	v_pk_mul_f32 v[30:31], v[30:31], v[250:251] op_sel_hi:[1,0]
	v_pk_mul_f32 v[32:33], v[32:33], v[250:251] op_sel_hi:[1,0]
	v_mul_f32_e32 v12, v12, v250
	v_mul_f32_e32 v159, v159, v250
.Ldq1_p0_nores:
	v_sub_f32_e32 v250, v98, v151
	v_exp_f32_e32 v98, v250
	v_sub_f32_e32 v161, v99, v151
	v_exp_f32_e32 v99, v161
	v_sub_f32_e32 v250, v100, v151
	v_exp_f32_e32 v100, v250
	v_sub_f32_e32 v161, v101, v151
	v_exp_f32_e32 v101, v161
	v_sub_f32_e32 v250, v102, v151
	v_exp_f32_e32 v102, v250
	v_sub_f32_e32 v161, v103, v151
	v_exp_f32_e32 v103, v161
	v_sub_f32_e32 v250, v104, v151
	v_exp_f32_e32 v104, v250
	v_sub_f32_e32 v161, v105, v151
	v_exp_f32_e32 v105, v161
	v_add_f32_e32 v12, v12, v98
	v_add_f32_e32 v159, v159, v99
	v_add_f32_e32 v12, v12, v100
	v_add_f32_e32 v159, v159, v101
	v_add_f32_e32 v12, v12, v102
	v_add_f32_e32 v159, v159, v103
	v_add_f32_e32 v12, v12, v104
	v_add_f32_e32 v159, v159, v105
	v_cvt_pk_bf16_f32 v98, v98, v99
	v_cvt_pk_bf16_f32 v99, v100, v101
	v_cvt_pk_bf16_f32 v100, v102, v103
	v_cvt_pk_bf16_f32 v101, v104, v105
	ds_read_b128 v[14:17], v175 offset:34848
	s_waitcnt lgkmcnt(4)
	v_mfma_f32_32x32x16_bf16 v[66:81], v[208:211], v[98:101], v[66:81]
	v_sub_f32_e32 v250, v106, v151
	v_exp_f32_e32 v106, v250
	v_sub_f32_e32 v161, v107, v151
	v_exp_f32_e32 v107, v161
	v_sub_f32_e32 v250, v108, v151
	v_exp_f32_e32 v108, v250
	v_sub_f32_e32 v161, v109, v151
	v_exp_f32_e32 v109, v161
	ds_read_b128 v[208:211], v175 offset:39456
	s_waitcnt lgkmcnt(4)
	v_mfma_f32_32x32x16_bf16 v[50:65], v[252:255], v[98:101], v[50:65]
	v_sub_f32_e32 v250, v110, v151
	v_exp_f32_e32 v110, v250
	v_sub_f32_e32 v161, v111, v151
	v_exp_f32_e32 v111, v161
	v_sub_f32_e32 v250, v112, v151
	v_exp_f32_e32 v112, v250
	v_sub_f32_e32 v161, v113, v151
	v_exp_f32_e32 v113, v161
	ds_read_b128 v[252:255], v175 offset:44064
	s_waitcnt lgkmcnt(4)
	v_mfma_f32_32x32x16_bf16 v[34:49], v[4:7], v[98:101], v[34:49]
	v_add_f32_e32 v12, v12, v106
	v_add_f32_e32 v159, v159, v107
	v_add_f32_e32 v12, v12, v108
	v_add_f32_e32 v159, v159, v109
	v_add_f32_e32 v12, v12, v110
	v_add_f32_e32 v159, v159, v111
	v_add_f32_e32 v12, v12, v112
	v_add_f32_e32 v159, v159, v113
	ds_read_b128 v[4:7], v175 offset:48672
	s_waitcnt lgkmcnt(4)
	v_mfma_f32_32x32x16_bf16 v[18:33], v[8:11], v[98:101], v[18:33]
	v_cvt_pk_bf16_f32 v106, v106, v107
	v_cvt_pk_bf16_f32 v107, v108, v109
	v_cvt_pk_bf16_f32 v108, v110, v111
	v_cvt_pk_bf16_f32 v109, v112, v113
	ds_read_b128 v[8:11], v175 offset:34880
	s_waitcnt lgkmcnt(4)
	v_mfma_f32_32x32x16_bf16 v[66:81], v[14:17], v[106:109], v[66:81]
	v_sub_f32_e32 v250, v82, v151
	v_exp_f32_e32 v82, v250
	v_sub_f32_e32 v161, v83, v151
	v_exp_f32_e32 v83, v161
	v_sub_f32_e32 v250, v84, v151
	v_exp_f32_e32 v84, v250
	v_sub_f32_e32 v161, v85, v151
	v_exp_f32_e32 v85, v161
	ds_read_b128 v[14:17], v175 offset:39488
	s_waitcnt lgkmcnt(4)
	v_mfma_f32_32x32x16_bf16 v[50:65], v[208:211], v[106:109], v[50:65]
	v_sub_f32_e32 v250, v86, v151
	v_exp_f32_e32 v86, v250
	v_sub_f32_e32 v161, v87, v151
	v_exp_f32_e32 v87, v161
	v_sub_f32_e32 v250, v88, v151
	v_exp_f32_e32 v88, v250
	v_sub_f32_e32 v161, v89, v151
	v_exp_f32_e32 v89, v161
	ds_read_b128 v[208:211], v175 offset:44096
	s_waitcnt lgkmcnt(4)
	v_mfma_f32_32x32x16_bf16 v[34:49], v[252:255], v[106:109], v[34:49]
	v_add_f32_e32 v12, v12, v82
	v_add_f32_e32 v159, v159, v83
	v_add_f32_e32 v12, v12, v84
	v_add_f32_e32 v159, v159, v85
	v_add_f32_e32 v12, v12, v86
	v_add_f32_e32 v159, v159, v87
	v_add_f32_e32 v12, v12, v88
	v_add_f32_e32 v159, v159, v89
	ds_read_b128 v[252:255], v175 offset:48704
	s_waitcnt lgkmcnt(4)
	v_mfma_f32_32x32x16_bf16 v[18:33], v[4:7], v[106:109], v[18:33]
	v_cvt_pk_bf16_f32 v82, v82, v83
	v_cvt_pk_bf16_f32 v83, v84, v85
	v_cvt_pk_bf16_f32 v84, v86, v87
	v_cvt_pk_bf16_f32 v85, v88, v89
	ds_read_b128 v[4:7], v175 offset:34912
	s_waitcnt lgkmcnt(4)
	v_mfma_f32_32x32x16_bf16 v[66:81], v[8:11], v[82:85], v[66:81]
	v_sub_f32_e32 v250, v90, v151
	v_exp_f32_e32 v90, v250
	v_sub_f32_e32 v161, v91, v151
	v_exp_f32_e32 v91, v161
	v_sub_f32_e32 v250, v92, v151
	v_exp_f32_e32 v92, v250
	v_sub_f32_e32 v161, v93, v151
	v_exp_f32_e32 v93, v161
	ds_read_b128 v[8:11], v175 offset:39520
	s_waitcnt lgkmcnt(4)
	v_mfma_f32_32x32x16_bf16 v[50:65], v[14:17], v[82:85], v[50:65]
	v_sub_f32_e32 v250, v94, v151
	v_exp_f32_e32 v94, v250
	v_sub_f32_e32 v161, v95, v151
	v_exp_f32_e32 v95, v161
	v_sub_f32_e32 v250, v96, v151
	v_exp_f32_e32 v96, v250
	v_sub_f32_e32 v161, v97, v151
	v_exp_f32_e32 v97, v161
	s_waitcnt vmcnt(7)
	ds_write_b128 v168, v[212:215] offset:17408
	s_waitcnt vmcnt(6)
	ds_write_b128 v170, v[216:219] offset:53248
	ds_read_b128 v[14:17], v175 offset:44128
	s_waitcnt lgkmcnt(6)
	v_mfma_f32_32x32x16_bf16 v[34:49], v[208:211], v[82:85], v[34:49]
	v_add_f32_e32 v12, v12, v90
	v_add_f32_e32 v159, v159, v91
	v_add_f32_e32 v12, v12, v92
	v_add_f32_e32 v159, v159, v93
	v_add_f32_e32 v12, v12, v94
	v_add_f32_e32 v159, v159, v95
	v_add_f32_e32 v12, v12, v96
	v_add_f32_e32 v159, v159, v97
	ds_read_b128 v[208:211], v175 offset:48736
	s_waitcnt lgkmcnt(6)
	v_mfma_f32_32x32x16_bf16 v[18:33], v[252:255], v[82:85], v[18:33]
	v_cvt_pk_bf16_f32 v90, v90, v91
	v_cvt_pk_bf16_f32 v91, v92, v93
	v_cvt_pk_bf16_f32 v92, v94, v95
	v_cvt_pk_bf16_f32 v93, v96, v97
	s_waitcnt vmcnt(5)
	ds_write_b128 v183, v[220:223] offset:17408
	s_waitcnt vmcnt(4)
	ds_write_b128 v188, v[224:227] offset:53248
	s_waitcnt lgkmcnt(7)
	v_mfma_f32_32x32x16_bf16 v[66:81], v[4:7], v[90:93], v[66:81]
	s_waitcnt vmcnt(3)
	ds_write_b128 v190, v[228:231] offset:17408
	s_waitcnt vmcnt(2)
	ds_write_b128 v193, v[232:235] offset:53248
	s_waitcnt lgkmcnt(8)
	v_mfma_f32_32x32x16_bf16 v[50:65], v[8:11], v[90:93], v[50:65]
	s_waitcnt lgkmcnt(5)
	v_mfma_f32_32x32x16_bf16 v[34:49], v[14:17], v[90:93], v[34:49]
	s_waitcnt vmcnt(1)
	ds_write_b128 v171, v[236:239] offset:17408
	s_waitcnt vmcnt(0)
	ds_write_b128 v173, v[240:243] offset:53248
	s_waitcnt lgkmcnt(6)
	v_mfma_f32_32x32x16_bf16 v[18:33], v[208:211], v[90:93], v[18:33]
	s_waitcnt lgkmcnt(0)
	s_barrier
	s_cmp_eq_u32 s38, s41
	s_cbranch_scc1 .Ldq1_exit
	s_mov_b32 s42, s41

.Ldq1_p1_addr:
	global_load_dwordx4 v[212:215], v2, s[24:25]
	global_load_dwordx4 v[216:219], v244, s[20:21]
	global_load_dwordx4 v[220:223], v162, s[24:25]
	global_load_dwordx4 v[224:227], v245, s[20:21]
	global_load_dwordx4 v[228:231], v160, s[24:25]
	global_load_dwordx4 v[232:235], v246, s[20:21]
	global_load_dwordx4 v[236:239], v158, s[24:25]
	global_load_dwordx4 v[240:243], v249, s[20:21]
	ds_read_b128 v[4:7], v174 offset:17408
	ds_read_b128 v[8:11], v174 offset:26112
	ds_read_b128 v[14:17], v174 offset:17440
	ds_read_b128 v[208:211], v174 offset:26144
	s_waitcnt vmcnt(8)
	s_waitcnt lgkmcnt(3)
	v_mfma_f32_32x32x16_bf16 v[98:113], v[4:7], v[126:129], 0
	ds_read_b128 v[252:255], v174 offset:17472
	s_waitcnt lgkmcnt(3)
	v_mfma_f32_32x32x16_bf16 v[82:97], v[8:11], v[126:129], 0
	ds_read_b128 v[4:7], v174 offset:26176
	s_waitcnt lgkmcnt(3)
	v_mfma_f32_32x32x16_bf16 v[98:113], v[14:17], v[122:125], v[98:113]
	ds_read_b128 v[8:11], v174 offset:17504
	s_waitcnt lgkmcnt(3)
	v_mfma_f32_32x32x16_bf16 v[82:97], v[208:211], v[122:125], v[82:97]
	ds_read_b128 v[14:17], v174 offset:26208
	s_waitcnt lgkmcnt(3)
	v_mfma_f32_32x32x16_bf16 v[98:113], v[252:255], v[118:121], v[98:113]
	ds_read_b128 v[208:211], v163 offset:34816
	s_waitcnt lgkmcnt(3)
	v_mfma_f32_32x32x16_bf16 v[82:97], v[4:7], v[118:121], v[82:97]
	ds_read_b128 v[252:255], v163 offset:39424
	s_waitcnt lgkmcnt(3)
	v_mfma_f32_32x32x16_bf16 v[98:113], v[8:11], v[114:117], v[98:113]
	ds_read_b128 v[4:7], v163 offset:44032
	s_waitcnt lgkmcnt(3)
	v_mfma_f32_32x32x16_bf16 v[82:97], v[14:17], v[114:117], v[82:97]
	ds_read_b128 v[8:11], v163 offset:48640
	v_add_f32_e32 v161, 0x41000000, v151
	s_nop 6
	v_max3_f32 v251, v98, v99, v100
	v_max3_f32 v13, v101, v102, v103
	v_max3_f32 v251, v251, v104, v105
	v_max3_f32 v13, v13, v106, v107
	v_max3_f32 v251, v251, v108, v109
	v_max3_f32 v13, v13, v110, v111
	v_max3_f32 v251, v251, v112, v113
	v_max3_f32 v13, v13, v82, v83
	v_max3_f32 v251, v251, v84, v85
	v_max3_f32 v13, v13, v86, v87
	v_max3_f32 v251, v251, v88, v89
	v_max3_f32 v13, v13, v90, v91
	v_max3_f32 v251, v251, v92, v93
	v_max3_f32 v13, v13, v94, v95
	v_max3_f32 v251, v251, v96, v97
	v_max_f32_e32 v251, v251, v13
	v_mov_b32_e32 v13, v251
	s_nop 1
	v_permlane32_swap_b32_e32 v251, v13
	v_max_f32_e32 v251, v251, v13
	v_cmp_gt_f32_e32 vcc, v251, v161
	s_cbranch_vccz .Ldq1_p1_nores
	v_max_f32_e32 v251, v151, v251
	v_sub_f32_e32 v250, v151, v251
	v_exp_f32_e32 v250, v250
	v_mov_b32_e32 v151, v251
	v_pk_mul_f32 v[66:67], v[66:67], v[250:251] op_sel_hi:[1,0]
	v_pk_mul_f32 v[68:69], v[68:69], v[250:251] op_sel_hi:[1,0]
	v_pk_mul_f32 v[70:71], v[70:71], v[250:251] op_sel_hi:[1,0]
	v_pk_mul_f32 v[72:73], v[72:73], v[250:251] op_sel_hi:[1,0]
	v_pk_mul_f32 v[74:75], v[74:75], v[250:251] op_sel_hi:[1,0]
	v_pk_mul_f32 v[76:77], v[76:77], v[250:251] op_sel_hi:[1,0]
	v_pk_mul_f32 v[78:79], v[78:79], v[250:251] op_sel_hi:[1,0]
	v_pk_mul_f32 v[80:81], v[80:81], v[250:251] op_sel_hi:[1,0]
	v_pk_mul_f32 v[50:51], v[50:51], v[250:251] op_sel_hi:[1,0]
	v_pk_mul_f32 v[52:53], v[52:53], v[250:251] op_sel_hi:[1,0]
	v_pk_mul_f32 v[54:55], v[54:55], v[250:251] op_sel_hi:[1,0]
	v_pk_mul_f32 v[56:57], v[56:57], v[250:251] op_sel_hi:[1,0]
	v_pk_mul_f32 v[58:59], v[58:59], v[250:251] op_sel_hi:[1,0]
	v_pk_mul_f32 v[60:61], v[60:61], v[250:251] op_sel_hi:[1,0]
	v_pk_mul_f32 v[62:63], v[62:63], v[250:251] op_sel_hi:[1,0]
	v_pk_mul_f32 v[64:65], v[64:65], v[250:251] op_sel_hi:[1,0]
	v_pk_mul_f32 v[34:35], v[34:35], v[250:251] op_sel_hi:[1,0]
	v_pk_mul_f32 v[36:37], v[36:37], v[250:251] op_sel_hi:[1,0]
	v_pk_mul_f32 v[38:39], v[38:39], v[250:251] op_sel_hi:[1,0]
	v_pk_mul_f32 v[40:41], v[40:41], v[250:251] op_sel_hi:[1,0]
	v_pk_mul_f32 v[42:43], v[42:43], v[250:251] op_sel_hi:[1,0]
	v_pk_mul_f32 v[44:45], v[44:45], v[250:251] op_sel_hi:[1,0]
	v_pk_mul_f32 v[46:47], v[46:47], v[250:251] op_sel_hi:[1,0]
	v_pk_mul_f32 v[48:49], v[48:49], v[250:251] op_sel_hi:[1,0]
	v_pk_mul_f32 v[18:19], v[18:19], v[250:251] op_sel_hi:[1,0]
	v_pk_mul_f32 v[20:21], v[20:21], v[250:251] op_sel_hi:[1,0]
	v_pk_mul_f32 v[22:23], v[22:23], v[250:251] op_sel_hi:[1,0]
	v_pk_mul_f32 v[24:25], v[24:25], v[250:251] op_sel_hi:[1,0]
	v_pk_mul_f32 v[26:27], v[26:27], v[250:251] op_sel_hi:[1,0]
	v_pk_mul_f32 v[28:29], v[28:29], v[250:251] op_sel_hi:[1,0]
	v_pk_mul_f32 v[30:31], v[30:31], v[250:251] op_sel_hi:[1,0]
	v_pk_mul_f32 v[32:33], v[32:33], v[250:251] op_sel_hi:[1,0]
	v_mul_f32_e32 v12, v12, v250
	v_mul_f32_e32 v159, v159, v250
.Ldq1_p1_nores:
	v_sub_f32_e32 v250, v98, v151
	v_exp_f32_e32 v98, v250
	v_sub_f32_e32 v161, v99, v151
	v_exp_f32_e32 v99, v161
	v_sub_f32_e32 v250, v100, v151
	v_exp_f32_e32 v100, v250
	v_sub_f32_e32 v161, v101, v151
	v_exp_f32_e32 v101, v161
	v_sub_f32_e32 v250, v102, v151
	v_exp_f32_e32 v102, v250
	v_sub_f32_e32 v161, v103, v151
	v_exp_f32_e32 v103, v161
	v_sub_f32_e32 v250, v104, v151
	v_exp_f32_e32 v104, v250
	v_sub_f32_e32 v161, v105, v151
	v_exp_f32_e32 v105, v161
	v_add_f32_e32 v12, v12, v98
	v_add_f32_e32 v159, v159, v99
	v_add_f32_e32 v12, v12, v100
	v_add_f32_e32 v159, v159, v101
	v_add_f32_e32 v12, v12, v102
	v_add_f32_e32 v159, v159, v103
	v_add_f32_e32 v12, v12, v104
	v_add_f32_e32 v159, v159, v105
	v_cvt_pk_bf16_f32 v98, v98, v99
	v_cvt_pk_bf16_f32 v99, v100, v101
	v_cvt_pk_bf16_f32 v100, v102, v103
	v_cvt_pk_bf16_f32 v101, v104, v105
	ds_read_b128 v[14:17], v163 offset:34848
	s_waitcnt lgkmcnt(4)
	v_mfma_f32_32x32x16_bf16 v[66:81], v[208:211], v[98:101], v[66:81]
	v_sub_f32_e32 v250, v106, v151
	v_exp_f32_e32 v106, v250
	v_sub_f32_e32 v161, v107, v151
	v_exp_f32_e32 v107, v161
	v_sub_f32_e32 v250, v108, v151
	v_exp_f32_e32 v108, v250
	v_sub_f32_e32 v161, v109, v151
	v_exp_f32_e32 v109, v161
	ds_read_b128 v[208:211], v163 offset:39456
	s_waitcnt lgkmcnt(4)
	v_mfma_f32_32x32x16_bf16 v[50:65], v[252:255], v[98:101], v[50:65]
	v_sub_f32_e32 v250, v110, v151
	v_exp_f32_e32 v110, v250
	v_sub_f32_e32 v161, v111, v151
	v_exp_f32_e32 v111, v161
	v_sub_f32_e32 v250, v112, v151
	v_exp_f32_e32 v112, v250
	v_sub_f32_e32 v161, v113, v151
	v_exp_f32_e32 v113, v161
	ds_read_b128 v[252:255], v163 offset:44064
	s_waitcnt lgkmcnt(4)
	v_mfma_f32_32x32x16_bf16 v[34:49], v[4:7], v[98:101], v[34:49]
	v_add_f32_e32 v12, v12, v106
	v_add_f32_e32 v159, v159, v107
	v_add_f32_e32 v12, v12, v108
	v_add_f32_e32 v159, v159, v109
	v_add_f32_e32 v12, v12, v110
	v_add_f32_e32 v159, v159, v111
	v_add_f32_e32 v12, v12, v112
	v_add_f32_e32 v159, v159, v113
	ds_read_b128 v[4:7], v163 offset:48672
	s_waitcnt lgkmcnt(4)
	v_mfma_f32_32x32x16_bf16 v[18:33], v[8:11], v[98:101], v[18:33]
	v_cvt_pk_bf16_f32 v106, v106, v107
	v_cvt_pk_bf16_f32 v107, v108, v109
	v_cvt_pk_bf16_f32 v108, v110, v111
	v_cvt_pk_bf16_f32 v109, v112, v113
	ds_read_b128 v[8:11], v163 offset:34880
	s_waitcnt lgkmcnt(4)
	v_mfma_f32_32x32x16_bf16 v[66:81], v[14:17], v[106:109], v[66:81]
	v_sub_f32_e32 v250, v82, v151
	v_exp_f32_e32 v82, v250
	v_sub_f32_e32 v161, v83, v151
	v_exp_f32_e32 v83, v161
	v_sub_f32_e32 v250, v84, v151
	v_exp_f32_e32 v84, v250
	v_sub_f32_e32 v161, v85, v151
	v_exp_f32_e32 v85, v161
	ds_read_b128 v[14:17], v163 offset:39488
	s_waitcnt lgkmcnt(4)
	v_mfma_f32_32x32x16_bf16 v[50:65], v[208:211], v[106:109], v[50:65]
	v_sub_f32_e32 v250, v86, v151
	v_exp_f32_e32 v86, v250
	v_sub_f32_e32 v161, v87, v151
	v_exp_f32_e32 v87, v161
	v_sub_f32_e32 v250, v88, v151
	v_exp_f32_e32 v88, v250
	v_sub_f32_e32 v161, v89, v151
	v_exp_f32_e32 v89, v161
	ds_read_b128 v[208:211], v163 offset:44096
	s_waitcnt lgkmcnt(4)
	v_mfma_f32_32x32x16_bf16 v[34:49], v[252:255], v[106:109], v[34:49]
	v_add_f32_e32 v12, v12, v82
	v_add_f32_e32 v159, v159, v83
	v_add_f32_e32 v12, v12, v84
	v_add_f32_e32 v159, v159, v85
	v_add_f32_e32 v12, v12, v86
	v_add_f32_e32 v159, v159, v87
	v_add_f32_e32 v12, v12, v88
	v_add_f32_e32 v159, v159, v89
	ds_read_b128 v[252:255], v163 offset:48704
	s_waitcnt lgkmcnt(4)
	v_mfma_f32_32x32x16_bf16 v[18:33], v[4:7], v[106:109], v[18:33]
	v_cvt_pk_bf16_f32 v82, v82, v83
	v_cvt_pk_bf16_f32 v83, v84, v85
	v_cvt_pk_bf16_f32 v84, v86, v87
	v_cvt_pk_bf16_f32 v85, v88, v89
	ds_read_b128 v[4:7], v163 offset:34912
	s_waitcnt lgkmcnt(4)
	v_mfma_f32_32x32x16_bf16 v[66:81], v[8:11], v[82:85], v[66:81]
	v_sub_f32_e32 v250, v90, v151
	v_exp_f32_e32 v90, v250
	v_sub_f32_e32 v161, v91, v151
	v_exp_f32_e32 v91, v161
	v_sub_f32_e32 v250, v92, v151
	v_exp_f32_e32 v92, v250
	v_sub_f32_e32 v161, v93, v151
	v_exp_f32_e32 v93, v161
	ds_read_b128 v[8:11], v163 offset:39520
	s_waitcnt lgkmcnt(4)
	v_mfma_f32_32x32x16_bf16 v[50:65], v[14:17], v[82:85], v[50:65]
	v_sub_f32_e32 v250, v94, v151
	v_exp_f32_e32 v94, v250
	v_sub_f32_e32 v161, v95, v151
	v_exp_f32_e32 v95, v161
	v_sub_f32_e32 v250, v96, v151
	v_exp_f32_e32 v96, v250
	v_sub_f32_e32 v161, v97, v151
	v_exp_f32_e32 v97, v161
	s_waitcnt vmcnt(7)
	ds_write_b128 v168, v[212:215]
	s_waitcnt vmcnt(6)
	ds_write_b128 v170, v[216:219] offset:34816
	ds_read_b128 v[14:17], v163 offset:44128
	s_waitcnt lgkmcnt(6)
	v_mfma_f32_32x32x16_bf16 v[34:49], v[208:211], v[82:85], v[34:49]
	v_add_f32_e32 v12, v12, v90
	v_add_f32_e32 v159, v159, v91
	v_add_f32_e32 v12, v12, v92
	v_add_f32_e32 v159, v159, v93
	v_add_f32_e32 v12, v12, v94
	v_add_f32_e32 v159, v159, v95
	v_add_f32_e32 v12, v12, v96
	v_add_f32_e32 v159, v159, v97
	ds_read_b128 v[208:211], v163 offset:48736
	s_waitcnt lgkmcnt(6)
	v_mfma_f32_32x32x16_bf16 v[18:33], v[252:255], v[82:85], v[18:33]
	v_cvt_pk_bf16_f32 v90, v90, v91
	v_cvt_pk_bf16_f32 v91, v92, v93
	v_cvt_pk_bf16_f32 v92, v94, v95
	v_cvt_pk_bf16_f32 v93, v96, v97
	s_waitcnt vmcnt(5)
	ds_write_b128 v183, v[220:223]
	s_waitcnt vmcnt(4)
	ds_write_b128 v188, v[224:227] offset:34816
	s_waitcnt lgkmcnt(7)
	v_mfma_f32_32x32x16_bf16 v[66:81], v[4:7], v[90:93], v[66:81]
	s_waitcnt vmcnt(3)
	ds_write_b128 v190, v[228:231]
	s_waitcnt vmcnt(2)
	ds_write_b128 v193, v[232:235] offset:34816
	s_waitcnt lgkmcnt(8)
	v_mfma_f32_32x32x16_bf16 v[50:65], v[8:11], v[90:93], v[50:65]
	s_waitcnt lgkmcnt(5)
	v_mfma_f32_32x32x16_bf16 v[34:49], v[14:17], v[90:93], v[34:49]
	s_waitcnt vmcnt(1)
	ds_write_b128 v171, v[236:239]
	s_waitcnt vmcnt(0)
	ds_write_b128 v173, v[240:243] offset:34816
	s_waitcnt lgkmcnt(6)
	v_mfma_f32_32x32x16_bf16 v[18:33], v[208:211], v[90:93], v[18:33]
	s_waitcnt lgkmcnt(0)
	s_barrier
	s_cmp_eq_u32 s38, s41
	s_cbranch_scc1 .Ldq1_exit
	s_mov_b32 s42, s41
	s_branch .Ldq1_p0_top
.Ldq1_exit:
	v_sub_u32_e32 v168, v168, v179
	v_lshrrev_b32_e32 v168, 1, v168
	v_sub_u32_e32 v183, v183, v179
	v_lshrrev_b32_e32 v183, 1, v183
	v_sub_u32_e32 v190, v190, v179
	v_lshrrev_b32_e32 v190, 1, v190
	v_sub_u32_e32 v171, v171, v179
	v_lshrrev_b32_e32 v171, 1, v171
	v_sub_u32_e32 v170, v170, v181
	v_sub_u32_e32 v188, v188, v181
	v_sub_u32_e32 v193, v193, v181
	v_sub_u32_e32 v173, v173, v181
	v_add_f32_e32 v12, v12, v159
